# P4: L2/MALL touch-prefetch of each tile's residual rows before its K loop
# baseline (speedup 1.0000x reference)
.LBB0_671:
	v_mbcnt_lo_u32_b32 v246, -1, 0
	v_mbcnt_hi_u32_b32 v246, -1, v246
	s_lshr_b32 s98, s35, 4
	v_add_u32_e32 v246, s98, v246
	v_and_b32_e32 v247, 7, v246
	v_lshrrev_b32_e32 v246, 3, v246
	s_lshl_b32 s98, s4, 8
	v_add_u32_e32 v246, s98, v246
	v_lshlrev_b32_e32 v248, 7, v247
	s_lshl_b32 s99, s55, 10
	v_add_u32_e32 v248, s99, v248
	v_mov_b32_e32 v249, 0
	v_lshl_add_u64 v[248:249], s[8:9], 0, v[248:249]
	s_movk_i32 s99, 0x2000
	v_mad_u64_u32 v[250:251], s[100:101], v246, s99, v[248:249]
	s_mov_b64 s[100:101], 0x80000
	global_load_dword v245, v[250:251], off
	v_lshl_add_u64 v[250:251], v[250:251], 0, s[100:101]
	global_load_dword v245, v[250:251], off
	v_lshl_add_u64 v[250:251], v[250:251], 0, s[100:101]
	global_load_dword v245, v[250:251], off
	v_lshl_add_u64 v[250:251], v[250:251], 0, s[100:101]
	global_load_dword v245, v[250:251], off
	s_add_u32 s6, s6, 0x80080
	s_addc_u32 s7, s7, 0
	s_add_u32 s5, s40, 0x100
	v_mov_b32_e32 v0, 0
	s_addc_u32 s25, s41, 0
	s_mov_b32 s56, -2
	v_mov_b32_e32 v1, v0
	v_mov_b32_e32 v2, v0
	v_mov_b32_e32 v3, v0
	v_mov_b32_e32 v4, v0
	v_mov_b32_e32 v5, v0
	v_mov_b32_e32 v6, v0
	v_mov_b32_e32 v7, v0
	v_mov_b32_e32 v16, v0
	v_mov_b32_e32 v17, v0
	v_mov_b32_e32 v18, v0
	v_mov_b32_e32 v19, v0
	v_mov_b32_e32 v20, v0
	v_mov_b32_e32 v21, v0
	v_mov_b32_e32 v22, v0
	v_mov_b32_e32 v23, v0
	v_mov_b32_e32 v32, v0
	v_mov_b32_e32 v33, v0
	v_mov_b32_e32 v34, v0
	v_mov_b32_e32 v35, v0
	v_mov_b32_e32 v36, v0
	v_mov_b32_e32 v37, v0
	v_mov_b32_e32 v38, v0
	v_mov_b32_e32 v39, v0
	v_mov_b32_e32 v48, v0
	v_mov_b32_e32 v49, v0
	v_mov_b32_e32 v50, v0
	v_mov_b32_e32 v51, v0
	v_mov_b32_e32 v52, v0
	v_mov_b32_e32 v53, v0
	v_mov_b32_e32 v54, v0
	v_mov_b32_e32 v55, v0
	v_mov_b32_e32 v8, v0
	v_mov_b32_e32 v9, v0
	v_mov_b32_e32 v10, v0
	v_mov_b32_e32 v11, v0
	v_mov_b32_e32 v12, v0
	v_mov_b32_e32 v13, v0
	v_mov_b32_e32 v14, v0
	v_mov_b32_e32 v15, v0
	v_mov_b32_e32 v24, v0
	v_mov_b32_e32 v25, v0
	v_mov_b32_e32 v26, v0
	v_mov_b32_e32 v27, v0
	v_mov_b32_e32 v28, v0
	v_mov_b32_e32 v29, v0
	v_mov_b32_e32 v30, v0
	v_mov_b32_e32 v31, v0
	v_mov_b32_e32 v40, v0
	v_mov_b32_e32 v41, v0
	v_mov_b32_e32 v42, v0
	v_mov_b32_e32 v43, v0
	v_mov_b32_e32 v44, v0
	v_mov_b32_e32 v45, v0
	v_mov_b32_e32 v46, v0
	v_mov_b32_e32 v47, v0
	v_mov_b32_e32 v56, v0
	v_mov_b32_e32 v57, v0
	v_mov_b32_e32 v58, v0
	v_mov_b32_e32 v59, v0
	v_mov_b32_e32 v60, v0
	v_mov_b32_e32 v61, v0
	v_mov_b32_e32 v62, v0
	v_mov_b32_e32 v63, v0
	v_mov_b32_e32 v64, v0
	v_mov_b32_e32 v65, v0
	v_mov_b32_e32 v66, v0
	v_mov_b32_e32 v67, v0
	v_mov_b32_e32 v68, v0
	v_mov_b32_e32 v69, v0
	v_mov_b32_e32 v70, v0
	v_mov_b32_e32 v71, v0
	v_mov_b32_e32 v80, v0
	v_mov_b32_e32 v81, v0
	v_mov_b32_e32 v82, v0
	v_mov_b32_e32 v83, v0
	v_mov_b32_e32 v84, v0
	v_mov_b32_e32 v85, v0
	v_mov_b32_e32 v86, v0
	v_mov_b32_e32 v87, v0
	v_mov_b32_e32 v96, v0
	v_mov_b32_e32 v97, v0
	v_mov_b32_e32 v98, v0
	v_mov_b32_e32 v99, v0
	v_mov_b32_e32 v100, v0
	v_mov_b32_e32 v101, v0
	v_mov_b32_e32 v102, v0
	v_mov_b32_e32 v103, v0
	v_mov_b32_e32 v112, v0
	v_mov_b32_e32 v113, v0
	v_mov_b32_e32 v114, v0
	v_mov_b32_e32 v115, v0
	v_mov_b32_e32 v116, v0
	v_mov_b32_e32 v117, v0
	v_mov_b32_e32 v118, v0
	v_mov_b32_e32 v119, v0
	v_mov_b32_e32 v72, v0
	v_mov_b32_e32 v73, v0
	v_mov_b32_e32 v74, v0
	v_mov_b32_e32 v75, v0
	v_mov_b32_e32 v76, v0
	v_mov_b32_e32 v77, v0
	v_mov_b32_e32 v78, v0
	v_mov_b32_e32 v79, v0
	v_mov_b32_e32 v88, v0
	v_mov_b32_e32 v89, v0
	v_mov_b32_e32 v90, v0
	v_mov_b32_e32 v91, v0
	v_mov_b32_e32 v92, v0
	v_mov_b32_e32 v93, v0
	v_mov_b32_e32 v94, v0
	v_mov_b32_e32 v95, v0
	v_mov_b32_e32 v104, v0
	v_mov_b32_e32 v105, v0
	v_mov_b32_e32 v106, v0
	v_mov_b32_e32 v107, v0
	v_mov_b32_e32 v108, v0
	v_mov_b32_e32 v109, v0
	v_mov_b32_e32 v110, v0
	v_mov_b32_e32 v111, v0
	v_mov_b32_e32 v120, v0
	v_mov_b32_e32 v121, v0
	v_mov_b32_e32 v122, v0
	v_mov_b32_e32 v123, v0
	v_mov_b32_e32 v124, v0
	v_mov_b32_e32 v125, v0
	v_mov_b32_e32 v126, v0
	v_mov_b32_e32 v127, v0
